# speedup vs baseline: 1.0058x; 1.0058x over previous
; __device__ __forceinline__ void tile_map(int t, int nM, int nN, int& pm, int& pn) {
;   int nwg = nM * nN, q = nwg / 8, r = nwg % 8, xcd = t % 8, off = t / 8;
;   int wgid = (xcd < r ? xcd * (q + 1) : r * (q + 1) + (xcd - r) * q) + off;
;   const int WGM = 8;
;   int nig = WGM * nN, gid = wgid / nig, fm = gid * WGM, gsz = min(nM - fm, WGM);
;   pm = __builtin_amdgcn_readfirstlane(fm + ((wgid % nig) % gsz)); pn = __builtin_amdgcn_readfirstlane((wgid % nig) / gsz);
; __device__ __forceinline__ void phase_g3(PP p, const int g_wid, int wrow0, int nN, u16* P, int ldp) {
;     ...
;   for (int t = bid; t < NMT * nN; t += gdim, par ^= 1) {
;     int pm, pn; tile_map(t, NMT, nN, pm, pn);
;     stage_rs(p, pm, par, tid);
;     f32x4 acc[2][2][4][2]; ZERO_ACC;
;     gemm256(p->Wm + (long)(wrow0 + pn * 256) * 1024, 1024, p->hb + (long)pm * 256 * 1024, 1024, 1024, acc, g_wid);
;     EPI_TID;
;     const float* rsl = RS_LDS(par);
;     u16* Pt = P + (long)pm * 256 * ldp + pn * 256;
;     const unsigned tok0 = wc * 32 + fr;
; #pragma unroll
;     for (int bj = 0; bj < 2; ++bj)
; #pragma unroll
;       for (int n = 0; n < 2; ++n) {
;         const unsigned tok = tok0 + bj * 128 + n * 16;
;         const float rs = rsl[tok];
;         u16* pp = Pt + tok * (unsigned)ldp + wr * 64 + SWAP_FOFF(fq);
; #pragma unroll
;         for (int ai = 0; ai < 2; ++ai)
; #pragma unroll
;           for (int mp = 0; mp < 4; mp += 2) {
;             const unsigned l0 = pack2(acc[ai][bj][mp][n][0] * rs, acc[ai][bj][mp][n][1] * rs), h0 = pack2(acc[ai][bj][mp][n][2] * rs, acc[ai][bj][mp][n][3] * rs);
;             const unsigned l1 = pack2(acc[ai][bj][mp + 1][n][0] * rs, acc[ai][bj][mp + 1][n][1] * rs), h1 = pack2(acc[ai][bj][mp + 1][n][2] * rs, acc[ai][bj][mp + 1][n][3] * rs);
;             *reinterpret_cast<uint4*>(pp + ai * 128 + mp * 16) = swap_pair(l0, h0, l1, h1);
.LBB0_307:
	v_readlane_b32 s2, v254, 56
	s_cmp_eq_u32 s2, 4
	s_cselect_b64 s[2:3], -1, 0
	s_and_b64 s[4:5], s[2:3], exec
	v_readlane_b32 s4, v254, 2
	s_cselect_b32 s10, 9, 8
	s_lshl_b32 s5, s4, 6
	s_mov_b32 s4, -1
	v_writelane_b32 v254, s5, 63
	s_waitcnt lgkmcnt(0)
	v_mbcnt_lo_u32_b32 v0, s4, 0
	v_mbcnt_hi_u32_b32 v0, s4, v0
	v_or_b32_e32 v142, s5, v0
	v_readlane_b32 s26, v254, 3
	s_movk_i32 s27, 0x600
	s_cmp_eq_u32 s10, 9
	s_cselect_b32 s27, 0x6d1, s27
	s_cmp_ge_i32 s26, s27
	s_cbranch_scc1 .LBB0_322
	s_and_b64 s[2:3], s[2:3], exec
	v_readlane_b32 s2, v254, 0
	v_readlane_b32 s3, v254, 1
	s_load_dwordx4 s[4:7], s[2:3], 0xc0
	s_load_dwordx2 s[8:9], s[2:3], 0xd0
	s_movk_i32 s2, 0x800
	s_cselect_b32 s29, 0x800, 0
	s_cselect_b32 s30, 0x900, s2
	s_lshl_b32 s34, s10, 3
	v_cvt_f32_ubyte0_e32 v0, s34
	v_rcp_iflag_f32_e32 v0, v0
	s_sub_i32 s10, 0, s34
	v_readlane_b32 s2, v254, 39
	s_lshr_b32 s31, s27, 3
	v_mul_f32_e32 v0, 0x4f7ffffe, v0
	v_cvt_u32_f32_e32 v0, v0
	v_lshl_add_u32 v143, v142, 2, s2
	s_movk_i32 s2, 0x100
	s_mov_b32 s28, 0
	v_readfirstlane_b32 s11, v0
	s_mul_i32 s10, s10, s11
	s_mul_hi_u32 s10, s11, s10
	s_add_i32 s38, s11, s10
	s_lshl_b32 s10, s30, 4
	s_mul_i32 s11, s30, 0x70
	s_and_b32 s35, s27, 7
	s_add_i32 s36, s31, 1
	v_cmp_gt_i32_e64 s[2:3], s2, v142
	s_lshl_b32 s37, s30, 8
	s_lshl_b32 s54, s10, 1
	s_lshl_b32 s10, s11, 1
	s_cmp_lg_u32 s34, 64
	s_cbranch_scc1 .Lg3_nocopy
	v_readlane_b32 s16, v254, 3
	v_readlane_b32 s18, v254, 0
	v_readlane_b32 s19, v254, 1
	s_load_dwordx2 s[18:19], s[18:19], 0xc0
	s_mul_i32 s17, s16, 0x1200
	s_add_u32 s17, s17, 0x8000000
	v_lshlrev_b32_e32 v200, 3, v142
	v_mov_b32_e32 v201, 0
	s_waitcnt lgkmcnt(0)
	s_add_u32 s18, s18, s17
	s_addc_u32 s19, s19, 0
	v_lshl_add_u64 v[202:203], s[18:19], 0, v[200:201]
	global_load_dwordx2 v[204:205], v[202:203], off
	s_add_i32 s17, s16, 0xc000
	s_lshl_b32 s17, s17, 12
	s_add_u32 s18, s8, s17
	s_addc_u32 s19, s9, 0
	v_lshl_add_u64 v[202:203], s[18:19], 0, v[200:201]
	s_waitcnt vmcnt(0)
	global_store_dwordx2 v[202:203], v[204:205], off
.Lg3_nocopy:
	s_branch .LBB0_310
.LBB0_309:
	s_or_b64 exec, exec, s[16:17]
	s_mov_b32 s11, -1
	s_movk_i32 s13, 0x60
	v_mbcnt_lo_u32_b32 v0, s11, 0
	v_mbcnt_hi_u32_b32 v0, s11, v0
	v_readlane_b32 s11, v254, 63
	s_nop 1
	v_or_b32_e32 v0, s11, v0
	s_lshl_b32 s11, s28, 10
	v_and_b32_e32 v130, 15, v0
	v_lshrrev_b32_e32 v131, 1, v0
	s_add_i32 s11, s11, 0
	v_and_or_b32 v134, v131, s13, v130
	v_ashrrev_i32_e32 v130, 2, v0
	v_and_b32_e32 v133, 16, v0
	v_lshrrev_b32_e32 v0, 2, v0
	v_lshl_add_u32 v132, v134, 2, s11
	s_mul_hi_i32 s13, s12, s37
	s_mul_i32 s12, s12, s37
	v_and_b32_e32 v0, 12, v0
	s_lshl_b64 s[12:13], s[12:13], 1
	v_cmp_eq_u32_e32 vcc, 0, v133
	v_add_u32_e32 v133, 12, v0
	v_add_u32_e32 v135, 0x20000, v132
	s_add_u32 s11, s8, s12
	v_cndmask_b32_e32 v0, v133, v0, vcc
	ds_read2_b32 v[132:133], v135 offset1:16
	s_addc_u32 s16, s9, s13
	s_ashr_i32 s15, s14, 31
	s_lshl_b64 s[12:13], s[14:15], 1
	s_add_u32 s12, s11, s12
	v_and_b32_e32 v130, 0xffffffc0, v130
	s_addc_u32 s13, s16, s13
	v_ashrrev_i32_e32 v131, 31, v130
	v_lshl_add_u64 v[130:131], v[130:131], 1, s[12:13]
	v_and_b32_e32 v247, 63, v142
	v_lshrrev_b32_e32 v250, 6, v142
	v_lshlrev_b32_e32 v250, 14, v250
	v_and_b32_e32 v244, 15, v247
	v_lshrrev_b32_e32 v245, 4, v247
	v_and_b32_e32 v251, 1, v245
	v_lshrrev_b32_e32 v245, 1, v245
	v_lshl_or_b32 v245, v251, 1, v245
	v_and_b32_e32 v251, 7, v244
	v_xor_b32_e32 v245, v245, v251
	v_lshlrev_b32_e32 v245, 4, v245
	v_lshl_add_u32 v244, v244, 7, v250
	v_add_u32_e32 v244, v244, v245
	v_xor_b32_e32 v245, 64, v244
	v_lshrrev_b32_e32 v246, 3, v247
	v_and_b32_e32 v251, 7, v247
	v_xor_b32_e32 v247, v251, v246
	v_lshlrev_b32_e32 v247, 4, v247
	v_lshl_add_u32 v250, v246, 7, v250
	v_add_u32_e32 v250, v250, v247
	v_lshrrev_b32_e32 v247, 1, v142
	v_and_b32_e32 v247, 0x60, v247
	v_add_u32_e32 v247, v247, v246
	v_mul_u32_u24_e32 v247, s30, v247
	v_lshlrev_b32_e32 v247, 1, v247
	v_lshl_add_u32 v248, v251, 4, v247
	v_mov_b32_e32 v249, 0
	v_lshl_add_u64 v[248:249], v[130:131], 0, v[248:249]
	v_mov_b32_e32 v246, v250
	v_lshlrev_b32_e32 v0, 1, v0
	s_waitcnt lgkmcnt(0)
	v_pk_mul_f32 v[102:103], v[102:103], v[132:133] op_sel_hi:[1,0]
	v_pk_mul_f32 v[104:105], v[104:105], v[132:133] op_sel_hi:[1,0]
	v_pk_mul_f32 v[98:99], v[98:99], v[132:133] op_sel_hi:[1,0]
	v_lshl_add_u64 v[130:131], v[130:131], 0, v[0:1]
	v_mul_u32_u24_e32 v0, s30, v134
	v_cvt_pk_bf16_f32 v102, v102, v103
	v_cvt_pk_bf16_f32 v103, v104, v105
	v_cvt_pk_bf16_f32 v104, v98, v99
	v_pk_mul_f32 v[98:99], v[100:101], v[132:133] op_sel_hi:[1,0]
	v_lshlrev_b32_e32 v0, 1, v0
	v_cvt_pk_bf16_f32 v105, v98, v99
	v_lshl_add_u64 v[130:131], v[130:131], 0, v[0:1]
	v_permlane16_swap_b32_e32 v102, v104
	v_permlane16_swap_b32_e32 v103, v105
	v_pk_mul_f32 v[98:99], v[126:127], v[132:133] op_sel_hi:[1,0]
	v_pk_mul_f32 v[100:101], v[128:129], v[132:133] op_sel_hi:[1,0]
	ds_write_b128 v245, v[102:105]
	v_cvt_pk_bf16_f32 v98, v98, v99
	v_cvt_pk_bf16_f32 v99, v100, v101
	v_pk_mul_f32 v[100:101], v[122:123], v[132:133] op_sel_hi:[1,0]
	v_pk_mul_f32 v[102:103], v[124:125], v[132:133] op_sel_hi:[1,0]
	v_cvt_pk_bf16_f32 v100, v100, v101
	v_cvt_pk_bf16_f32 v101, v102, v103
	s_nop 0
	v_permlane16_swap_b32_e32 v98, v100
	v_permlane16_swap_b32_e32 v99, v101
	ds_write_b128 v244, v[98:101] offset:2048
	v_mov_b32_e32 v0, v133
	v_pk_mul_f32 v[102:103], v[108:109], v[132:133] op_sel_hi:[1,0]
	v_pk_mul_f32 v[98:99], v[110:111], v[132:133] op_sel_hi:[1,0]
	v_pk_mul_f32 v[100:101], v[112:113], v[132:133] op_sel_hi:[1,0]
	v_cvt_pk_bf16_f32 v98, v98, v99
	v_cvt_pk_bf16_f32 v99, v100, v101
	v_pk_mul_f32 v[100:101], v[106:107], v[132:133] op_sel_hi:[1,0]
; __device__ __forceinline__ void phase_g3(PP p, const int g_wid, int wrow0, int nN, u16* P, int ldp) {
;     ...
;       for (int n = 0; n < 2; ++n) {
;         const unsigned tok = tok0 + bj * 128 + n * 16;
;         const float rs = rsl[tok];
;         u16* pp = Pt + tok * (unsigned)ldp + wr * 64 + SWAP_FOFF(fq);
; #pragma unroll
;         for (int ai = 0; ai < 2; ++ai)
; #pragma unroll
;           for (int mp = 0; mp < 4; mp += 2) {
;             const unsigned l0 = pack2(acc[ai][bj][mp][n][0] * rs, acc[ai][bj][mp][n][1] * rs), h0 = pack2(acc[ai][bj][mp][n][2] * rs, acc[ai][bj][mp][n][3] * rs);
;             const unsigned l1 = pack2(acc[ai][bj][mp + 1][n][0] * rs, acc[ai][bj][mp + 1][n][1] * rs), h1 = pack2(acc[ai][bj][mp + 1][n][2] * rs, acc[ai][bj][mp + 1][n][3] * rs);
;             *reinterpret_cast<uint4*>(pp + ai * 128 + mp * 16) = swap_pair(l0, h0, l1, h1);
;           }
	v_pk_mul_f32 v[70:71], v[70:71], v[0:1] op_sel_hi:[1,0]
	v_pk_mul_f32 v[72:73], v[72:73], v[0:1] op_sel_hi:[1,0]
	v_pk_mul_f32 v[66:67], v[66:67], v[0:1] op_sel_hi:[1,0]
	v_cvt_pk_bf16_f32 v100, v100, v101
	v_cvt_pk_bf16_f32 v101, v102, v103
	v_cvt_pk_bf16_f32 v70, v70, v71
	v_cvt_pk_bf16_f32 v71, v72, v73
	v_cvt_pk_bf16_f32 v72, v66, v67
	v_pk_mul_f32 v[66:67], v[68:69], v[0:1] op_sel_hi:[1,0]
	v_permlane16_swap_b32_e32 v98, v100
	v_permlane16_swap_b32_e32 v99, v101
	v_cvt_pk_bf16_f32 v73, v66, v67
	ds_write_b128 v245, v[98:101] offset:2048
	v_permlane16_swap_b32_e32 v70, v72
	s_nop 0
	v_lshl_add_u64 v[98:99], v[130:131], 0, s[54:55]
	v_permlane16_swap_b32_e32 v71, v73
	v_pk_mul_f32 v[66:67], v[94:95], v[0:1] op_sel_hi:[1,0]
	v_pk_mul_f32 v[68:69], v[96:97], v[0:1] op_sel_hi:[1,0]
	ds_write_b128 v245, v[70:73] offset:4096
	v_cvt_pk_bf16_f32 v66, v66, v67
	v_cvt_pk_bf16_f32 v67, v68, v69
	v_pk_mul_f32 v[68:69], v[90:91], v[0:1] op_sel_hi:[1,0]
	v_pk_mul_f32 v[70:71], v[92:93], v[0:1] op_sel_hi:[1,0]
	v_cvt_pk_bf16_f32 v68, v68, v69
	v_cvt_pk_bf16_f32 v69, v70, v71
	s_nop 0
	v_permlane16_swap_b32_e32 v66, v68
	v_permlane16_swap_b32_e32 v67, v69
	ds_write_b128 v244, v[66:69] offset:6144
	v_pk_mul_f32 v[70:71], v[76:77], v[0:1] op_sel_hi:[1,0]
	s_mov_b32 s11, s55
	v_pk_mul_f32 v[66:67], v[78:79], v[0:1] op_sel_hi:[1,0]
	v_pk_mul_f32 v[68:69], v[80:81], v[0:1] op_sel_hi:[1,0]
	v_cvt_pk_bf16_f32 v66, v66, v67
	v_cvt_pk_bf16_f32 v67, v68, v69
	v_pk_mul_f32 v[68:69], v[74:75], v[0:1] op_sel_hi:[1,0]
	v_pk_mul_f32 v[86:87], v[86:87], v[0:1] op_sel_hi:[1,0]
	v_cvt_pk_bf16_f32 v68, v68, v69
	v_cvt_pk_bf16_f32 v69, v70, v71
	s_nop 0
	v_permlane16_swap_b32_e32 v66, v68
	v_permlane16_swap_b32_e32 v67, v69
	ds_write_b128 v245, v[66:69] offset:6144
	ds_read2_b32 v[66:67], v135 offset0:128 offset1:144
	v_pk_mul_f32 v[88:89], v[88:89], v[0:1] op_sel_hi:[1,0]
	v_lshl_add_u64 v[68:69], v[98:99], 0, s[10:11]
	v_pk_mul_f32 v[82:83], v[82:83], v[0:1] op_sel_hi:[1,0]
	v_cvt_pk_bf16_f32 v86, v86, v87
	s_waitcnt lgkmcnt(0)
	v_pk_mul_f32 v[42:43], v[42:43], v[66:67] op_sel_hi:[1,0]
	v_pk_mul_f32 v[44:45], v[44:45], v[66:67] op_sel_hi:[1,0]
	v_pk_mul_f32 v[34:35], v[34:35], v[66:67] op_sel_hi:[1,0]
	v_cvt_pk_bf16_f32 v42, v42, v43
	v_cvt_pk_bf16_f32 v43, v44, v45
	v_cvt_pk_bf16_f32 v44, v34, v35
	v_pk_mul_f32 v[34:35], v[36:37], v[66:67] op_sel_hi:[1,0]
	s_nop 0
	v_permlane16_swap_b32_e32 v42, v44
	v_cvt_pk_bf16_f32 v45, v34, v35
	s_nop 1
	v_permlane16_swap_b32_e32 v43, v45
	v_pk_mul_f32 v[34:35], v[62:63], v[66:67] op_sel_hi:[1,0]
	v_pk_mul_f32 v[36:37], v[64:65], v[66:67] op_sel_hi:[1,0]
	ds_write_b128 v245, v[42:45] offset:8192
	v_cvt_pk_bf16_f32 v34, v34, v35
	v_cvt_pk_bf16_f32 v35, v36, v37
	v_pk_mul_f32 v[36:37], v[54:55], v[66:67] op_sel_hi:[1,0]
	v_pk_mul_f32 v[42:43], v[56:57], v[66:67] op_sel_hi:[1,0]
	v_cvt_pk_bf16_f32 v36, v36, v37
	v_cvt_pk_bf16_f32 v37, v42, v43
	s_nop 0
	v_permlane16_swap_b32_e32 v34, v36
	v_permlane16_swap_b32_e32 v35, v37
	v_cvt_pk_bf16_f32 v87, v88, v89
	v_cvt_pk_bf16_f32 v88, v82, v83
	v_pk_mul_f32 v[82:83], v[84:85], v[0:1] op_sel_hi:[1,0]
	ds_write_b128 v244, v[34:37] offset:10240
	v_mov_b32_e32 v0, v67
	v_pk_mul_f32 v[10:11], v[10:11], v[0:1] op_sel_hi:[1,0]
	v_pk_mul_f32 v[34:35], v[46:47], v[66:67] op_sel_hi:[1,0]
	v_pk_mul_f32 v[36:37], v[48:49], v[66:67] op_sel_hi:[1,0]
	v_cvt_pk_bf16_f32 v34, v34, v35
	v_cvt_pk_bf16_f32 v35, v36, v37
	v_pk_mul_f32 v[36:37], v[38:39], v[66:67] op_sel_hi:[1,0]
	v_pk_mul_f32 v[38:39], v[40:41], v[66:67] op_sel_hi:[1,0]
	v_pk_mul_f32 v[12:13], v[12:13], v[0:1] op_sel_hi:[1,0]
	v_pk_mul_f32 v[2:3], v[2:3], v[0:1] op_sel_hi:[1,0]
	v_cvt_pk_bf16_f32 v36, v36, v37
	v_cvt_pk_bf16_f32 v37, v38, v39
	v_cvt_pk_bf16_f32 v10, v10, v11
	v_cvt_pk_bf16_f32 v11, v12, v13
	v_cvt_pk_bf16_f32 v12, v2, v3
	v_pk_mul_f32 v[2:3], v[4:5], v[0:1] op_sel_hi:[1,0]
	v_permlane16_swap_b32_e32 v34, v36
	v_permlane16_swap_b32_e32 v35, v37
	v_cvt_pk_bf16_f32 v13, v2, v3
	ds_write_b128 v245, v[34:37] offset:10240
	v_permlane16_swap_b32_e32 v10, v12
	s_nop 0
	v_lshl_add_u64 v[34:35], v[68:69], 0, s[54:55]
	v_permlane16_swap_b32_e32 v11, v13
	v_pk_mul_f32 v[2:3], v[30:31], v[0:1] op_sel_hi:[1,0]
	v_pk_mul_f32 v[4:5], v[32:33], v[0:1] op_sel_hi:[1,0]
	ds_write_b128 v245, v[10:13] offset:12288
	v_cvt_pk_bf16_f32 v2, v2, v3
	v_cvt_pk_bf16_f32 v3, v4, v5
	v_pk_mul_f32 v[4:5], v[22:23], v[0:1] op_sel_hi:[1,0]
	v_pk_mul_f32 v[10:11], v[24:25], v[0:1] op_sel_hi:[1,0]
	v_cvt_pk_bf16_f32 v4, v4, v5
	v_cvt_pk_bf16_f32 v5, v10, v11
	s_nop 0
	v_permlane16_swap_b32_e32 v2, v4
	v_permlane16_swap_b32_e32 v3, v5
; __device__ __forceinline__ void phase_g3(PP p, const int g_wid, int wrow0, int nN, u16* P, int ldp) {
;     ...
; #pragma unroll
;     for (int bj = 0; bj < 2; ++bj)
; #pragma unroll
;       for (int n = 0; n < 2; ++n) {
;         const unsigned tok = tok0 + bj * 128 + n * 16;
;         const float rs = rsl[tok];
;         u16* pp = Pt + tok * (unsigned)ldp + wr * 64 + SWAP_FOFF(fq);
; #pragma unroll
;         for (int ai = 0; ai < 2; ++ai)
; #pragma unroll
;           for (int mp = 0; mp < 4; mp += 2) {
;             const unsigned l0 = pack2(acc[ai][bj][mp][n][0] * rs, acc[ai][bj][mp][n][1] * rs), h0 = pack2(acc[ai][bj][mp][n][2] * rs, acc[ai][bj][mp][n][3] * rs);
;             const unsigned l1 = pack2(acc[ai][bj][mp + 1][n][0] * rs, acc[ai][bj][mp + 1][n][1] * rs), h1 = pack2(acc[ai][bj][mp + 1][n][2] * rs, acc[ai][bj][mp + 1][n][3] * rs);
;             *reinterpret_cast<uint4*>(pp + ai * 128 + mp * 16) = swap_pair(l0, h0, l1, h1);
;           }
;       }
	v_pk_mul_f32 v[118:119], v[118:119], v[132:133] op_sel_hi:[1,0]
	v_pk_mul_f32 v[120:121], v[120:121], v[132:133] op_sel_hi:[1,0]
	v_pk_mul_f32 v[114:115], v[114:115], v[132:133] op_sel_hi:[1,0]
	v_pk_mul_f32 v[58:59], v[58:59], v[66:67] op_sel_hi:[1,0]
	v_pk_mul_f32 v[60:61], v[60:61], v[66:67] op_sel_hi:[1,0]
	v_pk_mul_f32 v[50:51], v[50:51], v[66:67] op_sel_hi:[1,0]
	v_pk_mul_f32 v[26:27], v[26:27], v[0:1] op_sel_hi:[1,0]
	v_pk_mul_f32 v[28:29], v[28:29], v[0:1] op_sel_hi:[1,0]
	v_pk_mul_f32 v[18:19], v[18:19], v[0:1] op_sel_hi:[1,0]
	ds_write_b128 v244, v[2:5] offset:14336
	v_cvt_pk_bf16_f32 v118, v118, v119
	v_cvt_pk_bf16_f32 v119, v120, v121
	v_pk_mul_f32 v[2:3], v[14:15], v[0:1] op_sel_hi:[1,0]
	v_pk_mul_f32 v[4:5], v[16:17], v[0:1] op_sel_hi:[1,0]
	v_cvt_pk_bf16_f32 v120, v114, v115
	v_pk_mul_f32 v[114:115], v[116:117], v[132:133] op_sel_hi:[1,0]
	v_cvt_pk_bf16_f32 v58, v58, v59
	v_cvt_pk_bf16_f32 v59, v60, v61
	v_cvt_pk_bf16_f32 v60, v50, v51
	v_pk_mul_f32 v[50:51], v[52:53], v[66:67] op_sel_hi:[1,0]
	v_cvt_pk_bf16_f32 v26, v26, v27
	v_cvt_pk_bf16_f32 v27, v28, v29
	v_cvt_pk_bf16_f32 v28, v18, v19
	v_pk_mul_f32 v[18:19], v[20:21], v[0:1] op_sel_hi:[1,0]
	v_cvt_pk_bf16_f32 v2, v2, v3
	v_cvt_pk_bf16_f32 v3, v4, v5
	v_pk_mul_f32 v[4:5], v[6:7], v[0:1] op_sel_hi:[1,0]
	v_pk_mul_f32 v[6:7], v[8:9], v[0:1] op_sel_hi:[1,0]
	v_readlane_b32 s11, v254, 4
	v_cvt_pk_bf16_f32 v121, v114, v115
	v_cvt_pk_bf16_f32 v89, v82, v83
	v_cvt_pk_bf16_f32 v61, v50, v51
	v_cvt_pk_bf16_f32 v29, v18, v19
	v_cvt_pk_bf16_f32 v4, v4, v5
	v_cvt_pk_bf16_f32 v5, v6, v7
	s_add_i32 s26, s26, s11
	s_xor_b32 s28, s28, 1
	v_permlane16_swap_b32_e32 v118, v120
	v_permlane16_swap_b32_e32 v119, v121
	v_permlane16_swap_b32_e32 v86, v88
	v_permlane16_swap_b32_e32 v87, v89
	v_permlane16_swap_b32_e32 v58, v60
	v_permlane16_swap_b32_e32 v59, v61
	v_permlane16_swap_b32_e32 v26, v28
	v_permlane16_swap_b32_e32 v27, v29
	v_permlane16_swap_b32_e32 v2, v4
	v_permlane16_swap_b32_e32 v3, v5
	ds_write_b128 v244, v[118:121]
	ds_write_b128 v244, v[86:89] offset:4096
	ds_write_b128 v244, v[58:61] offset:8192
	ds_write_b128 v244, v[26:29] offset:12288
	ds_write_b128 v245, v[2:5] offset:14336
	ds_read_b128 v[180:183], v246
	ds_read_b128 v[184:187], v246 offset:2048
	ds_read_b128 v[188:191], v246 offset:1024
	ds_read_b128 v[192:195], v246 offset:3072
	ds_read_b128 v[196:199], v246 offset:4096
	ds_read_b128 v[200:203], v246 offset:6144
	ds_read_b128 v[204:207], v246 offset:5120
	ds_read_b128 v[208:211], v246 offset:7168
	ds_read_b128 v[212:215], v246 offset:8192
	ds_read_b128 v[216:219], v246 offset:10240
	ds_read_b128 v[220:223], v246 offset:9216
	ds_read_b128 v[224:227], v246 offset:11264
	ds_read_b128 v[228:231], v246 offset:12288
	ds_read_b128 v[232:235], v246 offset:14336
	ds_read_b128 v[236:239], v246 offset:13312
	ds_read_b128 v[240:243], v246 offset:15360
	s_lshr_b32 s12, s54, 1
	s_mov_b32 s13, 0
	s_mul_i32 s14, s12, 13
	s_mov_b32 s15, 0
	s_waitcnt lgkmcnt(15)
	global_store_dwordx4 v[248:249], v[180:183], off
	s_waitcnt lgkmcnt(14)
	global_store_dwordx4 v[248:249], v[184:187], off offset:256
	v_lshl_add_u64 v[248:249], v[248:249], 0, s[12:13]
	s_waitcnt lgkmcnt(13)
	global_store_dwordx4 v[248:249], v[188:191], off
	s_waitcnt lgkmcnt(12)
	global_store_dwordx4 v[248:249], v[192:195], off offset:256
	v_lshl_add_u64 v[248:249], v[248:249], 0, s[12:13]
	s_waitcnt lgkmcnt(11)
	global_store_dwordx4 v[248:249], v[196:199], off
	s_waitcnt lgkmcnt(10)
	global_store_dwordx4 v[248:249], v[200:203], off offset:256
	v_lshl_add_u64 v[248:249], v[248:249], 0, s[12:13]
	s_waitcnt lgkmcnt(9)
	global_store_dwordx4 v[248:249], v[204:207], off
	s_waitcnt lgkmcnt(8)
	global_store_dwordx4 v[248:249], v[208:211], off offset:256
	v_lshl_add_u64 v[248:249], v[248:249], 0, s[14:15]
	s_waitcnt lgkmcnt(7)
	global_store_dwordx4 v[248:249], v[212:215], off
	s_waitcnt lgkmcnt(6)
	global_store_dwordx4 v[248:249], v[216:219], off offset:256
	v_lshl_add_u64 v[248:249], v[248:249], 0, s[12:13]
	s_waitcnt lgkmcnt(5)
	global_store_dwordx4 v[248:249], v[220:223], off
	s_waitcnt lgkmcnt(4)
	global_store_dwordx4 v[248:249], v[224:227], off offset:256
	v_lshl_add_u64 v[248:249], v[248:249], 0, s[12:13]
	s_waitcnt lgkmcnt(3)
	global_store_dwordx4 v[248:249], v[228:231], off
	s_waitcnt lgkmcnt(2)
	global_store_dwordx4 v[248:249], v[232:235], off offset:256
	v_lshl_add_u64 v[248:249], v[248:249], 0, s[12:13]
	s_waitcnt lgkmcnt(1)
	global_store_dwordx4 v[248:249], v[236:239], off
	s_waitcnt lgkmcnt(0)
	global_store_dwordx4 v[248:249], v[240:243], off offset:256
	s_barrier
	s_cmp_ge_i32 s26, s27
	s_cbranch_scc1 .LBB0_322

; #define hw_tid() ((g_wid << 6) | hw_lane())
; #define STA(P, br, kt) STAGE(P, A, aoff0, aoff1, lda, br, kt)
; #define STB(P, br, kt) STAGE(P, Bt, boff0, boff1, ldb, br, kt)
; #define BAR __builtin_amdgcn_s_barrier()
; __device__ __forceinline__ void gemm256(const u16* __restrict__ A, int lda, const u16* __restrict__ Bt, int ldb, int K,
;                                         f32x4 (&acc)[2][2][4][2], const int g_wid) {
;   int tid = hw_tid(); asm volatile("" : "+v"(tid));
;   const int wid = tid >> 6, lane = tid & 63, wr = wid >> 2, wc = wid & 3, fr = lane & 15, fq = lane >> 4;
;   int r0, c0, r1, c1;
;   stage_rc(tid * 16, r0, c0);
;   stage_rc(tid * 16 + 8192, r1, c1);
;   const int aoff0 = r0 * lda + c0, aoff1 = r1 * lda + c1, boff0 = r0 * ldb + c0, boff1 = r1 * ldb + c1;
;   bf16x8 At[4][2], B0[2][2], B1[2][2];
;   const int nt = K / BK;
;   STB(SB(0, 0), 0, 0); STA(SA(0, 0), 0, 0);
;   STB(SB(0, 1), HALF, 0); STA(SA(0, 1), HALF, 0);
;   if (wr == 1) BAR;
; __device__ __forceinline__ void phase_g3(PP p, const int g_wid, int wrow0, int nN, u16* P, int ldp) {
;     ...
;     int pm, pn; tile_map(t, NMT, nN, pm, pn);
;     stage_rs(p, pm, par, tid);
;     f32x4 acc[2][2][4][2]; ZERO_ACC;
;     gemm256(p->Wm + (long)(wrow0 + pn * 256) * 1024, 1024, p->hb + (long)pm * 256 * 1024, 1024, 1024, acc, g_wid);
.LBB0_316:
	s_or_b64 exec, exec, s[14:15]
	s_cmp_lt_i32 s11, 9
	s_cbranch_scc1 .Lg3_noextra
	s_mov_b32 s29, 0xfffff700
	v_readlane_b32 s16, v254, 0
	v_readlane_b32 s17, v254, 1
	s_load_dwordx2 s[8:9], s[16:17], 0xc0
	s_waitcnt lgkmcnt(0)
	s_add_u32 s8, s8, 0xfa7fee00
	s_addc_u32 s9, s9, -1
.Lg3_noextra:
	s_sext_i32_i16 s11, s11
	s_lshl_b32 s14, s11, 8
	s_mov_b32 s11, -1
	s_add_i32 s16, s14, s29
	v_mbcnt_lo_u32_b32 v0, s11, 0
	v_mbcnt_hi_u32_b32 v0, s11, v0
	v_readlane_b32 s11, v254, 63
	s_ashr_i32 s17, s16, 31
	s_lshl_b64 s[18:19], s[16:17], 11
	v_or_b32_e32 v0, s11, v0
	s_waitcnt lgkmcnt(0)
	s_add_u32 s16, s4, s18
	v_ashrrev_i32_e32 v2, 31, v0
	v_lshrrev_b32_e32 v2, 26, v2
	v_add_u32_e32 v2, v0, v2
	v_ashrrev_i32_e32 v10, 6, v2
	v_bfe_i32 v2, v0, 27, 1
	v_lshlrev_b32_e32 v16, 4, v0
	v_lshrrev_b32_e32 v2, 22, v2
	v_add_u32_e32 v2, v16, v2
	v_and_b32_e32 v2, 0xfffffc00, v2
	v_sub_u32_e32 v2, v16, v2
	v_lshrrev_b32_e32 v3, 4, v2
	v_bitop3_b32 v2, v3, v2, 32 bitop3:0x6c
	v_ashrrev_i32_e32 v4, 31, v2
	v_lshrrev_b32_e32 v4, 26, v4
	v_add_u32_e32 v4, v2, v4
	v_ashrrev_i32_e32 v11, 6, v4
	v_and_b32_e32 v4, 0xc0, v4
	v_sub_u32_e32 v2, v2, v4
	v_ashrrev_i16_sdwa v14, v151, sext(v2) dst_sel:DWORD dst_unused:UNUSED_PAD src0_sel:DWORD src1_sel:BYTE_0
	v_add_u32_e32 v2, 0x2000, v16
	v_ashrrev_i32_e32 v4, 31, v2
	v_lshrrev_b32_e32 v4, 22, v4
	v_add_u32_e32 v4, v2, v4
	v_ashrrev_i32_e32 v15, 10, v4
	v_mul_i32_i24_e32 v4, 0x400, v15
	v_sub_u32_e32 v2, v2, v4
	v_lshrrev_b32_e32 v4, 4, v2
	v_lshlrev_b32_e32 v5, 5, v10
	v_bitop3_b32 v2, v4, v2, 32 bitop3:0x6c
	v_and_b32_e32 v13, 32, v5
	v_ashrrev_i32_e32 v5, 31, v2
	v_lshrrev_b32_e32 v5, 26, v5
	v_lshlrev_b32_e32 v3, 3, v10
	v_add_u32_e32 v5, v2, v5
	v_and_b32_e32 v3, 0x3ffff0, v3
	v_lshlrev_b32_e32 v4, 3, v15
	v_ashrrev_i32_e32 v17, 6, v5
	v_and_b32_e32 v5, 0xc0, v5
	v_add_u32_e32 v3, v11, v3
	v_and_b32_e32 v4, 0x3ffff0, v4
	v_lshlrev_b32_e32 v6, 5, v15
	v_sub_u32_e32 v2, v2, v5
	s_addc_u32 s17, s5, s19
	s_ashr_i32 s13, s12, 31
	v_add_u32_e32 v4, v17, v4
	v_and_b32_e32 v18, 32, v6
	v_ashrrev_i16_sdwa v19, v151, sext(v2) dst_sel:DWORD dst_unused:UNUSED_PAD src0_sel:DWORD src1_sel:BYTE_0
	v_lshl_or_b32 v2, v3, 10, v13
	s_lshl_b64 s[20:21], s[12:13], 19
	v_add_u32_sdwa v132, v2, sext(v14) dst_sel:DWORD dst_unused:UNUSED_PAD src0_sel:DWORD src1_sel:WORD_0
	v_lshl_or_b32 v2, v4, 10, v18
	v_readlane_b32 s11, v254, 40
	s_add_u32 s22, s6, s20
	v_add_u32_sdwa v130, v2, sext(v19) dst_sel:DWORD dst_unused:UNUSED_PAD src0_sel:DWORD src1_sel:WORD_0
	v_ashrrev_i32_e32 v133, 31, v132
	v_add_u32_e32 v159, s11, v16
	s_addc_u32 s23, s7, s21
	v_lshlrev_b64 v[20:21], 1, v[132:133]
	v_readfirstlane_b32 s11, v159
	v_ashrrev_i32_e32 v131, 31, v130
	v_add_u32_e32 v160, 0x2000, v159
	v_lshl_add_u64 v[2:3], s[22:23], 0, v[20:21]
	s_mov_b32 m0, s11
	v_lshlrev_b64 v[22:23], 1, v[130:131]
	v_readfirstlane_b32 s11, v160
	v_add_u32_e32 v161, 0, v16
	global_load_lds_dwordx4 v[2:3], off
	v_lshl_add_u64 v[6:7], s[22:23], 0, v[22:23]
	s_mov_b32 m0, s11
	v_readfirstlane_b32 s11, v161
	v_add_u32_e32 v163, 0x2000, v161
	global_load_lds_dwordx4 v[6:7], off
	v_lshl_add_u64 v[8:9], s[16:17], 0, v[20:21]
	s_mov_b32 m0, s11
	v_readfirstlane_b32 s11, v163
	global_load_lds_dwordx4 v[8:9], off
	s_mov_b32 m0, s11
	v_readlane_b32 s11, v254, 41
	s_add_u32 s24, s22, 0x40000
	v_lshl_add_u64 v[4:5], s[16:17], 0, v[22:23]
	v_add_u32_e32 v164, s11, v16
	s_addc_u32 s25, s23, 0
	v_readfirstlane_b32 s11, v164
	global_load_lds_dwordx4 v[4:5], off
	v_lshl_add_u64 v[24:25], s[24:25], 0, v[20:21]
	s_mov_b32 m0, s11
	v_add_u32_e32 v165, 0x2000, v164
	global_load_lds_dwordx4 v[24:25], off
	v_lshl_add_u64 v[24:25], s[24:25], 0, v[22:23]
	v_readfirstlane_b32 s11, v165
	s_add_u32 s24, s16, 0x40000
	v_add_u32_e32 v166, 0x4000, v161
	s_mov_b32 m0, s11
	s_addc_u32 s25, s17, 0
	v_readfirstlane_b32 s11, v166
	v_add_u32_e32 v167, 0x6000, v161
	global_load_lds_dwordx4 v[24:25], off
	v_lshl_add_u64 v[20:21], s[24:25], 0, v[20:21]
	s_mov_b32 m0, s11
	v_readfirstlane_b32 s11, v167
	global_load_lds_dwordx4 v[20:21], off
	v_lshl_add_u64 v[20:21], s[24:25], 0, v[22:23]
	s_mov_b32 m0, s11
	v_ashrrev_i32_e32 v12, 8, v0
	global_load_lds_dwordx4 v[20:21], off
	v_cmp_eq_u32_e32 vcc, 1, v12
	s_and_saveexec_b64 s[24:25], vcc
	s_cbranch_execz .LBB0_318
	s_setprio 3
	s_barrier
